# hand-written EpiSc epilogue (P8 scores GEMM): packed exp2 argument scaling, 64-lane row-sum stores
# baseline (speedup 1.0000x reference)
.LBB0_1312:
	v_lshl_add_u32 v161, s36, 8, v144
	v_lshl_add_u32 v162, s24, 8, v146
	v_lshlrev_b32_e32 v163, 11, v161
	v_lshl_add_u32 v163, v162, 1, v163
	v_mbcnt_lo_u32_b32 v158, -1, 0
	v_mbcnt_hi_u32_b32 v158, -1, v158
	v_lshrrev_b32_e32 v159, 4, v158
	v_lshlrev_b32_e32 v160, 1, v159
	v_and_b32_e32 v160, 2, v160
	v_lshrrev_b32_e32 v159, 1, v159
	v_or_b32_e32 v160, v160, v159
	v_lshl_add_u32 v164, v160, 4, v161
	s_lshl_b32 s38, s24, 4
	s_lshl_b32 s39, s71, 2
	s_add_i32 s38, s38, s39
	v_lshl_add_u32 v164, v164, 6, s38
	v_add_u32_e32 v165, 0x2000, v164
	v_mov_b32_e32 v150, 0x3fb8aa3b
	v_mov_b32_e32 v151, 0x3fb8aa3b
	v_mov_b32_e32 v166, v163
	v_add_u32_e32 v167, 0x8000, v163
	v_add_u32_e32 v168, 0x10000, v163
	v_add_u32_e32 v169, 0x18000, v163
	v_add_u32_e32 v170, 0x40000, v163
	v_add_u32_e32 v171, 0x48000, v163
	v_add_u32_e32 v172, 0x50000, v163
	v_add_u32_e32 v173, 0x58000, v163
	s_waitcnt vmcnt(0)
	v_pk_mul_f32 v[124:125], v[124:125], v[150:151]
	v_pk_mul_f32 v[126:127], v[126:127], v[150:151]
	v_pk_mul_f32 v[120:121], v[120:121], v[150:151]
	v_pk_mul_f32 v[122:123], v[122:123], v[150:151]
	v_pk_mul_f32 v[116:117], v[116:117], v[150:151]
	v_pk_mul_f32 v[118:119], v[118:119], v[150:151]
	v_pk_mul_f32 v[112:113], v[112:113], v[150:151]
	v_pk_mul_f32 v[114:115], v[114:115], v[150:151]
	v_exp_f32_e32 v124, v124
	v_exp_f32_e32 v125, v125
	v_exp_f32_e32 v126, v126
	v_exp_f32_e32 v127, v127
	v_exp_f32_e32 v120, v120
	v_exp_f32_e32 v121, v121
	v_exp_f32_e32 v122, v122
	v_exp_f32_e32 v123, v123
	v_exp_f32_e32 v116, v116
	v_exp_f32_e32 v117, v117
	v_exp_f32_e32 v118, v118
	v_exp_f32_e32 v119, v119
	v_exp_f32_e32 v112, v112
	v_exp_f32_e32 v113, v113
	v_exp_f32_e32 v114, v114
	v_exp_f32_e32 v115, v115
	s_nop 0
	v_pk_add_f32 v[156:157], v[124:125], v[126:127]
	v_pk_add_f32 v[156:157], v[156:157], v[120:121]
	v_pk_add_f32 v[156:157], v[156:157], v[122:123]
	v_pk_add_f32 v[156:157], v[156:157], v[116:117]
	v_pk_add_f32 v[156:157], v[156:157], v[118:119]
	v_pk_add_f32 v[156:157], v[156:157], v[112:113]
	v_pk_add_f32 v[156:157], v[156:157], v[114:115]
	v_add_f32_e32 v152, v156, v157
	v_cvt_pk_bf16_f32 v124, v124, v125
	v_cvt_pk_bf16_f32 v125, v126, v127
	v_cvt_pk_bf16_f32 v126, v120, v121
	v_cvt_pk_bf16_f32 v127, v122, v123
	global_store_dwordx4 v166, v[124:127], s[16:17]
	v_cvt_pk_bf16_f32 v116, v116, v117
	v_cvt_pk_bf16_f32 v117, v118, v119
	v_cvt_pk_bf16_f32 v118, v112, v113
	v_cvt_pk_bf16_f32 v119, v114, v115
	global_store_dwordx4 v166, v[116:119], s[16:17] offset:256
	v_pk_mul_f32 v[108:109], v[108:109], v[150:151]
	v_pk_mul_f32 v[110:111], v[110:111], v[150:151]
	v_pk_mul_f32 v[104:105], v[104:105], v[150:151]
	v_pk_mul_f32 v[106:107], v[106:107], v[150:151]
	v_pk_mul_f32 v[100:101], v[100:101], v[150:151]
	v_pk_mul_f32 v[102:103], v[102:103], v[150:151]
	v_pk_mul_f32 v[96:97], v[96:97], v[150:151]
	v_pk_mul_f32 v[98:99], v[98:99], v[150:151]
	v_exp_f32_e32 v108, v108
	v_exp_f32_e32 v109, v109
	v_exp_f32_e32 v110, v110
	v_exp_f32_e32 v111, v111
	v_exp_f32_e32 v104, v104
	v_exp_f32_e32 v105, v105
	v_exp_f32_e32 v106, v106
	v_exp_f32_e32 v107, v107
	v_exp_f32_e32 v100, v100
	v_exp_f32_e32 v101, v101
	v_exp_f32_e32 v102, v102
	v_exp_f32_e32 v103, v103
	v_exp_f32_e32 v96, v96
	v_exp_f32_e32 v97, v97
	v_exp_f32_e32 v98, v98
	v_exp_f32_e32 v99, v99
	s_nop 0
	v_pk_add_f32 v[156:157], v[108:109], v[110:111]
	v_pk_add_f32 v[156:157], v[156:157], v[104:105]
	v_pk_add_f32 v[156:157], v[156:157], v[106:107]
	v_pk_add_f32 v[156:157], v[156:157], v[100:101]
	v_pk_add_f32 v[156:157], v[156:157], v[102:103]
	v_pk_add_f32 v[156:157], v[156:157], v[96:97]
	v_pk_add_f32 v[156:157], v[156:157], v[98:99]
	v_add_f32_e32 v153, v156, v157
	v_cvt_pk_bf16_f32 v108, v108, v109
	v_cvt_pk_bf16_f32 v109, v110, v111
	v_cvt_pk_bf16_f32 v110, v104, v105
	v_cvt_pk_bf16_f32 v111, v106, v107
	global_store_dwordx4 v167, v[108:111], s[16:17]
	v_cvt_pk_bf16_f32 v100, v100, v101
	v_cvt_pk_bf16_f32 v101, v102, v103
	v_cvt_pk_bf16_f32 v102, v96, v97
	v_cvt_pk_bf16_f32 v103, v98, v99
	global_store_dwordx4 v167, v[100:103], s[16:17] offset:256
	v_pk_mul_f32 v[92:93], v[92:93], v[150:151]
	v_pk_mul_f32 v[94:95], v[94:95], v[150:151]
	v_pk_mul_f32 v[88:89], v[88:89], v[150:151]
	v_pk_mul_f32 v[90:91], v[90:91], v[150:151]
	v_pk_mul_f32 v[84:85], v[84:85], v[150:151]
	v_pk_mul_f32 v[86:87], v[86:87], v[150:151]
	v_pk_mul_f32 v[80:81], v[80:81], v[150:151]
	v_pk_mul_f32 v[82:83], v[82:83], v[150:151]
	v_exp_f32_e32 v92, v92
	v_exp_f32_e32 v93, v93
	v_exp_f32_e32 v94, v94
	v_exp_f32_e32 v95, v95
	v_exp_f32_e32 v88, v88
	v_exp_f32_e32 v89, v89
	v_exp_f32_e32 v90, v90
	v_exp_f32_e32 v91, v91
	v_exp_f32_e32 v84, v84
	v_exp_f32_e32 v85, v85
	v_exp_f32_e32 v86, v86
	v_exp_f32_e32 v87, v87
	v_exp_f32_e32 v80, v80
	v_exp_f32_e32 v81, v81
	v_exp_f32_e32 v82, v82
	v_exp_f32_e32 v83, v83
	s_nop 0
	v_pk_add_f32 v[156:157], v[92:93], v[94:95]
	v_pk_add_f32 v[156:157], v[156:157], v[88:89]
	v_pk_add_f32 v[156:157], v[156:157], v[90:91]
	v_pk_add_f32 v[156:157], v[156:157], v[84:85]
	v_pk_add_f32 v[156:157], v[156:157], v[86:87]
	v_pk_add_f32 v[156:157], v[156:157], v[80:81]
	v_pk_add_f32 v[156:157], v[156:157], v[82:83]
	v_add_f32_e32 v154, v156, v157
	v_cvt_pk_bf16_f32 v92, v92, v93
	v_cvt_pk_bf16_f32 v93, v94, v95
	v_cvt_pk_bf16_f32 v94, v88, v89
	v_cvt_pk_bf16_f32 v95, v90, v91
	global_store_dwordx4 v168, v[92:95], s[16:17]
	v_cvt_pk_bf16_f32 v84, v84, v85
	v_cvt_pk_bf16_f32 v85, v86, v87
	v_cvt_pk_bf16_f32 v86, v80, v81
	v_cvt_pk_bf16_f32 v87, v82, v83
	global_store_dwordx4 v168, v[84:87], s[16:17] offset:256
	v_pk_mul_f32 v[76:77], v[76:77], v[150:151]
	v_pk_mul_f32 v[78:79], v[78:79], v[150:151]
	v_pk_mul_f32 v[72:73], v[72:73], v[150:151]
	v_pk_mul_f32 v[74:75], v[74:75], v[150:151]
	v_pk_mul_f32 v[68:69], v[68:69], v[150:151]
	v_pk_mul_f32 v[70:71], v[70:71], v[150:151]
	v_pk_mul_f32 v[64:65], v[64:65], v[150:151]
	v_pk_mul_f32 v[66:67], v[66:67], v[150:151]
	v_exp_f32_e32 v76, v76
	v_exp_f32_e32 v77, v77
	v_exp_f32_e32 v78, v78
	v_exp_f32_e32 v79, v79
	v_exp_f32_e32 v72, v72
	v_exp_f32_e32 v73, v73
	v_exp_f32_e32 v74, v74
	v_exp_f32_e32 v75, v75
	v_exp_f32_e32 v68, v68
	v_exp_f32_e32 v69, v69
	v_exp_f32_e32 v70, v70
	v_exp_f32_e32 v71, v71
	v_exp_f32_e32 v64, v64
	v_exp_f32_e32 v65, v65
	v_exp_f32_e32 v66, v66
	v_exp_f32_e32 v67, v67
	s_nop 0
	v_pk_add_f32 v[156:157], v[76:77], v[78:79]
	v_pk_add_f32 v[156:157], v[156:157], v[72:73]
	v_pk_add_f32 v[156:157], v[156:157], v[74:75]
	v_pk_add_f32 v[156:157], v[156:157], v[68:69]
	v_pk_add_f32 v[156:157], v[156:157], v[70:71]
	v_pk_add_f32 v[156:157], v[156:157], v[64:65]
	v_pk_add_f32 v[156:157], v[156:157], v[66:67]
	v_add_f32_e32 v155, v156, v157
	v_cvt_pk_bf16_f32 v76, v76, v77
	v_cvt_pk_bf16_f32 v77, v78, v79
	v_cvt_pk_bf16_f32 v78, v72, v73
	v_cvt_pk_bf16_f32 v79, v74, v75
	global_store_dwordx4 v169, v[76:79], s[16:17]
	v_cvt_pk_bf16_f32 v68, v68, v69
	v_cvt_pk_bf16_f32 v69, v70, v71
	v_cvt_pk_bf16_f32 v70, v64, v65
	v_cvt_pk_bf16_f32 v71, v66, v67
	global_store_dwordx4 v169, v[68:71], s[16:17] offset:256
	s_nop 1
	v_permlane32_swap_b32_e32 v152, v153
	v_permlane32_swap_b32_e32 v154, v155
	v_add_f32_e32 v152, v152, v153
	v_add_f32_e32 v154, v154, v155
	s_nop 1
	v_permlane16_swap_b32_e32 v152, v154
	v_add_f32_e32 v152, v152, v154
	global_store_dword v164, v152, s[18:19]
	v_pk_mul_f32 v[60:61], v[60:61], v[150:151]
	v_pk_mul_f32 v[62:63], v[62:63], v[150:151]
	v_pk_mul_f32 v[56:57], v[56:57], v[150:151]
	v_pk_mul_f32 v[58:59], v[58:59], v[150:151]
	v_pk_mul_f32 v[52:53], v[52:53], v[150:151]
	v_pk_mul_f32 v[54:55], v[54:55], v[150:151]
	v_pk_mul_f32 v[48:49], v[48:49], v[150:151]
	v_pk_mul_f32 v[50:51], v[50:51], v[150:151]
	v_exp_f32_e32 v60, v60
	v_exp_f32_e32 v61, v61
	v_exp_f32_e32 v62, v62
	v_exp_f32_e32 v63, v63
	v_exp_f32_e32 v56, v56
	v_exp_f32_e32 v57, v57
	v_exp_f32_e32 v58, v58
	v_exp_f32_e32 v59, v59
	v_exp_f32_e32 v52, v52
	v_exp_f32_e32 v53, v53
	v_exp_f32_e32 v54, v54
	v_exp_f32_e32 v55, v55
	v_exp_f32_e32 v48, v48
	v_exp_f32_e32 v49, v49
	v_exp_f32_e32 v50, v50
	v_exp_f32_e32 v51, v51
	s_nop 0
	v_pk_add_f32 v[156:157], v[60:61], v[62:63]
	v_pk_add_f32 v[156:157], v[156:157], v[56:57]
	v_pk_add_f32 v[156:157], v[156:157], v[58:59]
	v_pk_add_f32 v[156:157], v[156:157], v[52:53]
	v_pk_add_f32 v[156:157], v[156:157], v[54:55]
	v_pk_add_f32 v[156:157], v[156:157], v[48:49]
	v_pk_add_f32 v[156:157], v[156:157], v[50:51]
	v_add_f32_e32 v152, v156, v157
	v_cvt_pk_bf16_f32 v60, v60, v61
	v_cvt_pk_bf16_f32 v61, v62, v63
	v_cvt_pk_bf16_f32 v62, v56, v57
	v_cvt_pk_bf16_f32 v63, v58, v59
	global_store_dwordx4 v170, v[60:63], s[16:17]
	v_cvt_pk_bf16_f32 v52, v52, v53
	v_cvt_pk_bf16_f32 v53, v54, v55
	v_cvt_pk_bf16_f32 v54, v48, v49
	v_cvt_pk_bf16_f32 v55, v50, v51
	global_store_dwordx4 v170, v[52:55], s[16:17] offset:256
	v_pk_mul_f32 v[44:45], v[44:45], v[150:151]
	v_pk_mul_f32 v[46:47], v[46:47], v[150:151]
	v_pk_mul_f32 v[40:41], v[40:41], v[150:151]
	v_pk_mul_f32 v[42:43], v[42:43], v[150:151]
	v_pk_mul_f32 v[36:37], v[36:37], v[150:151]
	v_pk_mul_f32 v[38:39], v[38:39], v[150:151]
	v_pk_mul_f32 v[32:33], v[32:33], v[150:151]
	v_pk_mul_f32 v[34:35], v[34:35], v[150:151]
	v_exp_f32_e32 v44, v44
	v_exp_f32_e32 v45, v45
	v_exp_f32_e32 v46, v46
	v_exp_f32_e32 v47, v47
	v_exp_f32_e32 v40, v40
	v_exp_f32_e32 v41, v41
	v_exp_f32_e32 v42, v42
	v_exp_f32_e32 v43, v43
	v_exp_f32_e32 v36, v36
	v_exp_f32_e32 v37, v37
	v_exp_f32_e32 v38, v38
	v_exp_f32_e32 v39, v39
	v_exp_f32_e32 v32, v32
	v_exp_f32_e32 v33, v33
	v_exp_f32_e32 v34, v34
	v_exp_f32_e32 v35, v35
	s_nop 0
	v_pk_add_f32 v[156:157], v[44:45], v[46:47]
	v_pk_add_f32 v[156:157], v[156:157], v[40:41]
	v_pk_add_f32 v[156:157], v[156:157], v[42:43]
	v_pk_add_f32 v[156:157], v[156:157], v[36:37]
	v_pk_add_f32 v[156:157], v[156:157], v[38:39]
	v_pk_add_f32 v[156:157], v[156:157], v[32:33]
	v_pk_add_f32 v[156:157], v[156:157], v[34:35]
	v_add_f32_e32 v153, v156, v157
	v_cvt_pk_bf16_f32 v44, v44, v45
	v_cvt_pk_bf16_f32 v45, v46, v47
	v_cvt_pk_bf16_f32 v46, v40, v41
	v_cvt_pk_bf16_f32 v47, v42, v43
	global_store_dwordx4 v171, v[44:47], s[16:17]
	v_cvt_pk_bf16_f32 v36, v36, v37
	v_cvt_pk_bf16_f32 v37, v38, v39
	v_cvt_pk_bf16_f32 v38, v32, v33
	v_cvt_pk_bf16_f32 v39, v34, v35
	global_store_dwordx4 v171, v[36:39], s[16:17] offset:256
	v_pk_mul_f32 v[28:29], v[28:29], v[150:151]
	v_pk_mul_f32 v[30:31], v[30:31], v[150:151]
	v_pk_mul_f32 v[24:25], v[24:25], v[150:151]
	v_pk_mul_f32 v[26:27], v[26:27], v[150:151]
	v_pk_mul_f32 v[20:21], v[20:21], v[150:151]
	v_pk_mul_f32 v[22:23], v[22:23], v[150:151]
	v_pk_mul_f32 v[16:17], v[16:17], v[150:151]
	v_pk_mul_f32 v[18:19], v[18:19], v[150:151]
	v_exp_f32_e32 v28, v28
	v_exp_f32_e32 v29, v29
	v_exp_f32_e32 v30, v30
	v_exp_f32_e32 v31, v31
	v_exp_f32_e32 v24, v24
	v_exp_f32_e32 v25, v25
	v_exp_f32_e32 v26, v26
	v_exp_f32_e32 v27, v27
	v_exp_f32_e32 v20, v20
	v_exp_f32_e32 v21, v21
	v_exp_f32_e32 v22, v22
	v_exp_f32_e32 v23, v23
	v_exp_f32_e32 v16, v16
	v_exp_f32_e32 v17, v17
	v_exp_f32_e32 v18, v18
	v_exp_f32_e32 v19, v19
	s_nop 0
	v_pk_add_f32 v[156:157], v[28:29], v[30:31]
	v_pk_add_f32 v[156:157], v[156:157], v[24:25]
	v_pk_add_f32 v[156:157], v[156:157], v[26:27]
	v_pk_add_f32 v[156:157], v[156:157], v[20:21]
	v_pk_add_f32 v[156:157], v[156:157], v[22:23]
	v_pk_add_f32 v[156:157], v[156:157], v[16:17]
	v_pk_add_f32 v[156:157], v[156:157], v[18:19]
	v_add_f32_e32 v154, v156, v157
	v_cvt_pk_bf16_f32 v28, v28, v29
	v_cvt_pk_bf16_f32 v29, v30, v31
	v_cvt_pk_bf16_f32 v30, v24, v25
	v_cvt_pk_bf16_f32 v31, v26, v27
	global_store_dwordx4 v172, v[28:31], s[16:17]
	v_cvt_pk_bf16_f32 v20, v20, v21
	v_cvt_pk_bf16_f32 v21, v22, v23
	v_cvt_pk_bf16_f32 v22, v16, v17
	v_cvt_pk_bf16_f32 v23, v18, v19
	global_store_dwordx4 v172, v[20:23], s[16:17] offset:256
	v_pk_mul_f32 v[12:13], v[12:13], v[150:151]
	v_pk_mul_f32 v[14:15], v[14:15], v[150:151]
	v_pk_mul_f32 v[8:9], v[8:9], v[150:151]
	v_pk_mul_f32 v[10:11], v[10:11], v[150:151]
	v_pk_mul_f32 v[4:5], v[4:5], v[150:151]
	v_pk_mul_f32 v[6:7], v[6:7], v[150:151]
	v_pk_mul_f32 v[0:1], v[0:1], v[150:151]
	v_pk_mul_f32 v[2:3], v[2:3], v[150:151]
	v_exp_f32_e32 v12, v12
	v_exp_f32_e32 v13, v13
	v_exp_f32_e32 v14, v14
	v_exp_f32_e32 v15, v15
	v_exp_f32_e32 v8, v8
	v_exp_f32_e32 v9, v9
	v_exp_f32_e32 v10, v10
	v_exp_f32_e32 v11, v11
	v_exp_f32_e32 v4, v4
	v_exp_f32_e32 v5, v5
	v_exp_f32_e32 v6, v6
	v_exp_f32_e32 v7, v7
	v_exp_f32_e32 v0, v0
	v_exp_f32_e32 v1, v1
	v_exp_f32_e32 v2, v2
	v_exp_f32_e32 v3, v3
	s_nop 0
	v_pk_add_f32 v[156:157], v[12:13], v[14:15]
	v_pk_add_f32 v[156:157], v[156:157], v[8:9]
	v_pk_add_f32 v[156:157], v[156:157], v[10:11]
	v_pk_add_f32 v[156:157], v[156:157], v[4:5]
	v_pk_add_f32 v[156:157], v[156:157], v[6:7]
	v_pk_add_f32 v[156:157], v[156:157], v[0:1]
	v_pk_add_f32 v[156:157], v[156:157], v[2:3]
	v_add_f32_e32 v155, v156, v157
	v_cvt_pk_bf16_f32 v12, v12, v13
	v_cvt_pk_bf16_f32 v13, v14, v15
	v_cvt_pk_bf16_f32 v14, v8, v9
	v_cvt_pk_bf16_f32 v15, v10, v11
	global_store_dwordx4 v173, v[12:15], s[16:17]
	v_cvt_pk_bf16_f32 v4, v4, v5
	v_cvt_pk_bf16_f32 v5, v6, v7
	v_cvt_pk_bf16_f32 v6, v0, v1
	v_cvt_pk_bf16_f32 v7, v2, v3
	global_store_dwordx4 v173, v[4:7], s[16:17] offset:256
	s_nop 1
	v_permlane32_swap_b32_e32 v152, v153
	v_permlane32_swap_b32_e32 v154, v155
	v_add_f32_e32 v152, v152, v153
	v_add_f32_e32 v154, v154, v155
	s_nop 1
	v_permlane16_swap_b32_e32 v152, v154
	v_add_f32_e32 v152, v152, v154
	global_store_dword v165, v152, s[18:19]
	s_and_b64 vcc, exec, s[8:9]
	s_mov_b64 s[8:9], -1
	s_cbranch_vccnz .LBB0_1297
	s_and_b64 vcc, exec, s[0:1]
	s_cbranch_vccnz .LBB0_1296
	s_barrier
	s_branch .LBB0_1296
